# window-attention unit epilogue rewritten by hand: normalised output staged through a wave-private LDS transpose and stored as 8 dwordx4 rows per lane instead of 64 2-byte stores
# speedup vs baseline: 1.0046x; 1.0046x over previous
; __device__ __forceinline__ int crow(int r, int hi) { return (r & 3) + 8 * (r >> 2) + 4 * hi; }
; template <int MODE, int ORD> ...
;     ...
;   if (hi == 0) li_l[r32] = l_reg; asm volatile("s_waitcnt lgkmcnt(0)" ::: "memory");
;   float rli[16];
; #pragma unroll
;   for (int r = 0; r < 16; ++r) rli[r] = __builtin_amdgcn_rcpf(li_l[crow(r, hi)]);
;   if (MODE == 1) {
;     bf16* Ow = Ob + (long)(wq * 32) * LDO;
; #pragma unroll
;     for (int r = 0; r < 16; ++r) { const int orow = crow(r, hi);
; #pragma unroll
;       for (int d0 = 0; d0 < 4; ++d0) { __hip_bfloat16 bv = __float2bfloat16(o[d0][r] * rli[r]); Ow[(long)orow * LDO + d0 * 32 + r32] = *reinterpret_cast<bf16*>(&bv); } }
.LBB0_208:
	s_or_b64 exec, exec, s[0:1]
	s_waitcnt lgkmcnt(0)
	ds_read_b128 v[0:3], v199
	ds_read_b128 v[4:7], v199 offset:32
	ds_read_b128 v[80:83], v199 offset:64
	ds_read_b128 v[8:11], v199 offset:96
	s_lshl_b64 s[0:1], s[4:5], 20
	s_add_u32 s0, s33, s0
	s_addc_u32 s1, s3, s1
	s_lshl_b32 s4, s10, 1
	s_add_u32 s4, s0, s4
	s_addc_u32 s5, s1, 0
	s_ashr_i32 s7, s6, 31
	s_lshl_b64 s[0:1], s[6:7], 12
	s_add_u32 s0, s4, s0
	s_addc_u32 s1, s5, s1
	s_add_u32 s0, s0, 0x800
	s_addc_u32 s1, s1, 0
	v_readfirstlane_b32 s4, v244
	s_lshr_b32 s4, s4, 6
	s_lshl_b32 s6, s4, 13
	v_lshlrev_b32_e32 v12, 1, v177
	v_lshl_add_u32 v12, v176, 10, v12
	v_add_u32_e32 v12, s6, v12
	v_lshl_or_b32 v14, v176, 5, v177
	v_lshl_add_u32 v13, v14, 4, s6
	v_lshrrev_b32_e32 v15, 4, v14
	v_and_b32_e32 v14, 15, v14
	v_lshlrev_b32_e32 v14, 4, v14
	v_lshl_or_b32 v14, v15, 12, v14
	s_waitcnt lgkmcnt(0)
	v_rcp_f32_e32 v0, v0
	v_rcp_f32_e32 v1, v1
	v_rcp_f32_e32 v2, v2
	v_rcp_f32_e32 v3, v3
	v_rcp_f32_e32 v4, v4
	v_rcp_f32_e32 v5, v5
	v_rcp_f32_e32 v6, v6
	v_rcp_f32_e32 v7, v7
	v_rcp_f32_e32 v80, v80
	v_rcp_f32_e32 v81, v81
	v_rcp_f32_e32 v82, v82
	v_rcp_f32_e32 v83, v83
	v_rcp_f32_e32 v8, v8
	v_rcp_f32_e32 v9, v9
	v_rcp_f32_e32 v10, v10
	v_rcp_f32_e32 v11, v11
	s_barrier
	v_mul_f32_e32 v32, v32, v0
	v_mul_f32_e32 v64, v64, v0
	v_mul_f32_e32 v48, v48, v0
	v_mul_f32_e32 v16, v16, v0
	v_cvt_pk_bf16_f32 v32, v32, v32
	v_cvt_pk_bf16_f32 v64, v64, v64
	v_cvt_pk_bf16_f32 v48, v48, v48
	v_cvt_pk_bf16_f32 v16, v16, v16
	ds_write_b16 v12, v32
	ds_write_b16 v12, v64 offset:64
	ds_write_b16 v12, v48 offset:128
	ds_write_b16 v12, v16 offset:192
	v_mul_f32_e32 v33, v33, v1
	v_mul_f32_e32 v65, v65, v1
	v_mul_f32_e32 v49, v49, v1
	v_mul_f32_e32 v17, v17, v1
	v_cvt_pk_bf16_f32 v33, v33, v33
	v_cvt_pk_bf16_f32 v65, v65, v65
	v_cvt_pk_bf16_f32 v49, v49, v49
	v_cvt_pk_bf16_f32 v17, v17, v17
	ds_write_b16 v12, v33 offset:256
	ds_write_b16 v12, v65 offset:320
	ds_write_b16 v12, v49 offset:384
	ds_write_b16 v12, v17 offset:448
	v_mul_f32_e32 v34, v34, v2
	v_mul_f32_e32 v66, v66, v2
	v_mul_f32_e32 v50, v50, v2
	v_mul_f32_e32 v18, v18, v2
	v_cvt_pk_bf16_f32 v34, v34, v34
	v_cvt_pk_bf16_f32 v66, v66, v66
	v_cvt_pk_bf16_f32 v50, v50, v50
	v_cvt_pk_bf16_f32 v18, v18, v18
	ds_write_b16 v12, v34 offset:512
	ds_write_b16 v12, v66 offset:576
	ds_write_b16 v12, v50 offset:640
	ds_write_b16 v12, v18 offset:704
	v_mul_f32_e32 v35, v35, v3
	v_mul_f32_e32 v67, v67, v3
	v_mul_f32_e32 v51, v51, v3
	v_mul_f32_e32 v19, v19, v3
	v_cvt_pk_bf16_f32 v35, v35, v35
	v_cvt_pk_bf16_f32 v67, v67, v67
	v_cvt_pk_bf16_f32 v51, v51, v51
	v_cvt_pk_bf16_f32 v19, v19, v19
	ds_write_b16 v12, v35 offset:768
	ds_write_b16 v12, v67 offset:832
	ds_write_b16 v12, v51 offset:896
	ds_write_b16 v12, v19 offset:960
	v_mul_f32_e32 v36, v36, v4
	v_mul_f32_e32 v68, v68, v4
	v_mul_f32_e32 v52, v52, v4
	v_mul_f32_e32 v20, v20, v4
	v_cvt_pk_bf16_f32 v36, v36, v36
	v_cvt_pk_bf16_f32 v68, v68, v68
	v_cvt_pk_bf16_f32 v52, v52, v52
	v_cvt_pk_bf16_f32 v20, v20, v20
	ds_write_b16 v12, v36 offset:2048
	ds_write_b16 v12, v68 offset:2112
	ds_write_b16 v12, v52 offset:2176
	ds_write_b16 v12, v20 offset:2240
	v_mul_f32_e32 v37, v37, v5
	v_mul_f32_e32 v69, v69, v5
	v_mul_f32_e32 v53, v53, v5
	v_mul_f32_e32 v21, v21, v5
	v_cvt_pk_bf16_f32 v37, v37, v37
	v_cvt_pk_bf16_f32 v69, v69, v69
	v_cvt_pk_bf16_f32 v53, v53, v53
	v_cvt_pk_bf16_f32 v21, v21, v21
	ds_write_b16 v12, v37 offset:2304
	ds_write_b16 v12, v69 offset:2368
	ds_write_b16 v12, v53 offset:2432
	ds_write_b16 v12, v21 offset:2496
	v_mul_f32_e32 v38, v38, v6
	v_mul_f32_e32 v70, v70, v6
	v_mul_f32_e32 v54, v54, v6
	v_mul_f32_e32 v22, v22, v6
	v_cvt_pk_bf16_f32 v38, v38, v38
	v_cvt_pk_bf16_f32 v70, v70, v70
	v_cvt_pk_bf16_f32 v54, v54, v54
	v_cvt_pk_bf16_f32 v22, v22, v22
	ds_write_b16 v12, v38 offset:2560
	ds_write_b16 v12, v70 offset:2624
	ds_write_b16 v12, v54 offset:2688
	ds_write_b16 v12, v22 offset:2752
	v_mul_f32_e32 v39, v39, v7
	v_mul_f32_e32 v71, v71, v7
	v_mul_f32_e32 v55, v55, v7
	v_mul_f32_e32 v23, v23, v7
	v_cvt_pk_bf16_f32 v39, v39, v39
	v_cvt_pk_bf16_f32 v71, v71, v71
	v_cvt_pk_bf16_f32 v55, v55, v55
	v_cvt_pk_bf16_f32 v23, v23, v23
	ds_write_b16 v12, v39 offset:2816
	ds_write_b16 v12, v71 offset:2880
	ds_write_b16 v12, v55 offset:2944
	ds_write_b16 v12, v23 offset:3008
	v_mul_f32_e32 v40, v40, v80
; __device__ __forceinline__ int crow(int r, int hi) { return (r & 3) + 8 * (r >> 2) + 4 * hi; }
; template <int MODE, int ORD> ...
;     ...
;   if (hi == 0) li_l[r32] = l_reg; asm volatile("s_waitcnt lgkmcnt(0)" ::: "memory");
;   float rli[16];
; #pragma unroll
;   for (int r = 0; r < 16; ++r) rli[r] = __builtin_amdgcn_rcpf(li_l[crow(r, hi)]);
;   if (MODE == 1) {
;     bf16* Ow = Ob + (long)(wq * 32) * LDO;
; #pragma unroll
;     for (int r = 0; r < 16; ++r) { const int orow = crow(r, hi);
; #pragma unroll
;       for (int d0 = 0; d0 < 4; ++d0) { __hip_bfloat16 bv = __float2bfloat16(o[d0][r] * rli[r]); Ow[(long)orow * LDO + d0 * 32 + r32] = *reinterpret_cast<bf16*>(&bv); } }
	v_mul_f32_e32 v72, v72, v80
	v_mul_f32_e32 v56, v56, v80
	v_mul_f32_e32 v24, v24, v80
	v_cvt_pk_bf16_f32 v40, v40, v40
	v_cvt_pk_bf16_f32 v72, v72, v72
	v_cvt_pk_bf16_f32 v56, v56, v56
	v_cvt_pk_bf16_f32 v24, v24, v24
	ds_write_b16 v12, v40 offset:4096
	ds_write_b16 v12, v72 offset:4160
	ds_write_b16 v12, v56 offset:4224
	ds_write_b16 v12, v24 offset:4288
	v_mul_f32_e32 v41, v41, v81
	v_mul_f32_e32 v73, v73, v81
	v_mul_f32_e32 v57, v57, v81
	v_mul_f32_e32 v25, v25, v81
	v_cvt_pk_bf16_f32 v41, v41, v41
	v_cvt_pk_bf16_f32 v73, v73, v73
	v_cvt_pk_bf16_f32 v57, v57, v57
	v_cvt_pk_bf16_f32 v25, v25, v25
	ds_write_b16 v12, v41 offset:4352
	ds_write_b16 v12, v73 offset:4416
	ds_write_b16 v12, v57 offset:4480
	ds_write_b16 v12, v25 offset:4544
	v_mul_f32_e32 v42, v42, v82
	v_mul_f32_e32 v74, v74, v82
	v_mul_f32_e32 v58, v58, v82
	v_mul_f32_e32 v26, v26, v82
	v_cvt_pk_bf16_f32 v42, v42, v42
	v_cvt_pk_bf16_f32 v74, v74, v74
	v_cvt_pk_bf16_f32 v58, v58, v58
	v_cvt_pk_bf16_f32 v26, v26, v26
	ds_write_b16 v12, v42 offset:4608
	ds_write_b16 v12, v74 offset:4672
	ds_write_b16 v12, v58 offset:4736
	ds_write_b16 v12, v26 offset:4800
	v_mul_f32_e32 v43, v43, v83
	v_mul_f32_e32 v75, v75, v83
	v_mul_f32_e32 v59, v59, v83
	v_mul_f32_e32 v27, v27, v83
	v_cvt_pk_bf16_f32 v43, v43, v43
	v_cvt_pk_bf16_f32 v75, v75, v75
	v_cvt_pk_bf16_f32 v59, v59, v59
	v_cvt_pk_bf16_f32 v27, v27, v27
	ds_write_b16 v12, v43 offset:4864
	ds_write_b16 v12, v75 offset:4928
	ds_write_b16 v12, v59 offset:4992
	ds_write_b16 v12, v27 offset:5056
	v_mul_f32_e32 v44, v44, v8
	v_mul_f32_e32 v76, v76, v8
	v_mul_f32_e32 v60, v60, v8
	v_mul_f32_e32 v28, v28, v8
	v_cvt_pk_bf16_f32 v44, v44, v44
	v_cvt_pk_bf16_f32 v76, v76, v76
	v_cvt_pk_bf16_f32 v60, v60, v60
	v_cvt_pk_bf16_f32 v28, v28, v28
	ds_write_b16 v12, v44 offset:6144
	ds_write_b16 v12, v76 offset:6208
	ds_write_b16 v12, v60 offset:6272
	ds_write_b16 v12, v28 offset:6336
	v_mul_f32_e32 v45, v45, v9
	v_mul_f32_e32 v77, v77, v9
	v_mul_f32_e32 v61, v61, v9
	v_mul_f32_e32 v29, v29, v9
	v_cvt_pk_bf16_f32 v45, v45, v45
	v_cvt_pk_bf16_f32 v77, v77, v77
	v_cvt_pk_bf16_f32 v61, v61, v61
	v_cvt_pk_bf16_f32 v29, v29, v29
	ds_write_b16 v12, v45 offset:6400
	ds_write_b16 v12, v77 offset:6464
	ds_write_b16 v12, v61 offset:6528
	ds_write_b16 v12, v29 offset:6592
	v_mul_f32_e32 v46, v46, v10
	v_mul_f32_e32 v78, v78, v10
	v_mul_f32_e32 v62, v62, v10
	v_mul_f32_e32 v30, v30, v10
	v_cvt_pk_bf16_f32 v46, v46, v46
	v_cvt_pk_bf16_f32 v78, v78, v78
	v_cvt_pk_bf16_f32 v62, v62, v62
	v_cvt_pk_bf16_f32 v30, v30, v30
	ds_write_b16 v12, v46 offset:6656
	ds_write_b16 v12, v78 offset:6720
	ds_write_b16 v12, v62 offset:6784
	ds_write_b16 v12, v30 offset:6848
	v_mul_f32_e32 v47, v47, v11
	v_mul_f32_e32 v79, v79, v11
	v_mul_f32_e32 v63, v63, v11
	v_mul_f32_e32 v31, v31, v11
	v_cvt_pk_bf16_f32 v47, v47, v47
	v_cvt_pk_bf16_f32 v79, v79, v79
	v_cvt_pk_bf16_f32 v63, v63, v63
	v_cvt_pk_bf16_f32 v31, v31, v31
	ds_write_b16 v12, v47 offset:6912
	ds_write_b16 v12, v79 offset:6976
	ds_write_b16 v12, v63 offset:7040
	ds_write_b16 v12, v31 offset:7104
	s_waitcnt lgkmcnt(0)
	ds_read_b128 v[16:19], v13
	ds_read_b128 v[20:23], v13 offset:1024
	ds_read_b128 v[24:27], v13 offset:2048
	ds_read_b128 v[28:31], v13 offset:3072
	ds_read_b128 v[32:35], v13 offset:4096
	ds_read_b128 v[36:39], v13 offset:5120
	ds_read_b128 v[40:43], v13 offset:6144
	ds_read_b128 v[44:47], v13 offset:7168
	s_waitcnt lgkmcnt(7)
	global_store_dwordx4 v14, v[16:19], s[0:1]
	s_add_u32 s0, s0, 0x4000
	s_addc_u32 s1, s1, 0
	s_waitcnt lgkmcnt(6)
	global_store_dwordx4 v14, v[20:23], s[0:1]
	s_add_u32 s0, s0, 0x4000
	s_addc_u32 s1, s1, 0
	s_waitcnt lgkmcnt(5)
	global_store_dwordx4 v14, v[24:27], s[0:1]
	s_add_u32 s0, s0, 0x4000
	s_addc_u32 s1, s1, 0
	s_waitcnt lgkmcnt(4)
	global_store_dwordx4 v14, v[28:31], s[0:1]
	s_add_u32 s0, s0, 0x4000
	s_addc_u32 s1, s1, 0
	s_waitcnt lgkmcnt(3)
	global_store_dwordx4 v14, v[32:35], s[0:1]
	s_add_u32 s0, s0, 0x4000
	s_addc_u32 s1, s1, 0
	s_waitcnt lgkmcnt(2)
	global_store_dwordx4 v14, v[36:39], s[0:1]
	s_add_u32 s0, s0, 0x4000
	s_addc_u32 s1, s1, 0
	s_waitcnt lgkmcnt(1)
	global_store_dwordx4 v14, v[40:43], s[0:1]
	s_add_u32 s0, s0, 0x4000
	s_addc_u32 s1, s1, 0
	s_waitcnt lgkmcnt(0)
	global_store_dwordx4 v14, v[44:47], s[0:1]
	s_setprio 0
	s_add_i32 s49, s49, s52
	s_cmpk_gt_i32 s49, 0x4ff
	s_cbranch_scc1 .LBB0_245
